# A/B items remapped so each WG owns two adjacent items and an XCC owns one sequence (halo L2 reuse)
# baseline (speedup 1.0000x reference)
.LBB0_428:
	s_or_b64 exec, exec, s[2:3]
	s_abs_i32 s0, s46
	v_cvt_f32_u32_e32 v1, s0
	s_sub_i32 s1, 0, s0
	s_movk_i32 s3, 0x352
	s_mov_b32 s15, 0
	v_rcp_iflag_f32_e32 v1, v1
	s_mov_b32 s66, 0x2100000
	s_mov_b32 s64, s58
	v_mov_b32_e32 v155, 0
	v_mul_f32_e32 v1, 0x4f7ffffe, v1
	v_cvt_u32_f32_e32 v1, v1
	v_mov_b32_e32 v180, 1
	v_mov_b64_e32 v[156:157], 0x39c
	v_mov_b64_e32 v[158:159], 0x39b
	v_readfirstlane_b32 s2, v1
	s_mul_i32 s1, s1, s2
	s_mul_hi_u32 s1, s2, s1
	s_add_i32 s2, s2, s1
	s_mul_hi_u32 s1, s2, 0x39c
	s_mul_i32 s1, s1, s0
	s_sub_i32 s1, 0x39c, s1
	s_sub_i32 s7, s1, s0
	s_cmp_ge_u32 s1, s0
	s_cselect_b32 s1, s7, s1
	s_sub_i32 s7, s1, s0
	s_cmp_ge_u32 s1, s0
	s_cselect_b32 s1, s7, s1
	s_sub_i32 s20, s46, s1
	s_sub_i32 s7, s24, s1
	s_cmp_gt_i32 s7, -1
	s_cselect_b64 s[8:9], -1, 0
	v_writelane_b32 v244, s8, 12
	s_cmp_lg_u32 s1, 0
	v_mbcnt_hi_u32_b32 v181, -1, v40
	v_writelane_b32 v244, s9, 13
	s_cselect_b64 s[8:9], -1, 0
	s_bitcmp0_b32 s7, 0
	v_writelane_b32 v244, s8, 14
	s_cselect_b32 s14, s3, 0x6a4
	s_cmpk_lt_u32 s7, 0x1c0
	v_writelane_b32 v244, s9, 15
	s_cselect_b64 s[8:9], -1, 0
	v_writelane_b32 v244, s8, 16
	v_mov_b64_e32 v[160:161], 0xff
	v_mov_b64_e32 v[162:163], 0x100
	v_writelane_b32 v244, s9, 17
	s_add_u32 s8, s74, 0xd80000
	s_addc_u32 s9, s75, 0
	v_writelane_b32 v244, s8, 18
	s_mov_b32 s75, 0x20000
	s_mov_b32 s74, 0x4200000
	v_writelane_b32 v244, s9, 19
	s_add_u32 s8, s72, 0x1000
	s_addc_u32 s9, s73, 0
	v_writelane_b32 v244, s8, 20
	s_add_u32 s3, s52, 0x700000
	s_mov_b32 s67, s75
	v_writelane_b32 v244, s9, 21
	v_writelane_b32 v244, s3, 22
	s_addc_u32 s3, s53, 0
	s_cmp_lg_u64 s[72:73], 0
	v_writelane_b32 v244, s3, 23
	s_cselect_b64 s[8:9], -1, 0
	v_writelane_b32 v244, s8, 24
	s_cmpk_lt_i32 s7, 0x80
	s_mov_b32 s72, s60
	v_writelane_b32 v244, s9, 25
	s_cselect_b64 s[8:9], -1, 0
	s_add_u32 s26, s94, 0x400000
	s_addc_u32 s27, s95, 0
	s_add_u32 s21, s54, 0x200000
	v_writelane_b32 v244, s7, 26
	s_addc_u32 s28, s55, 0
	v_writelane_b32 v244, s8, 27
	s_cmpk_lt_i32 s24, 0x39c
	s_movk_i32 s25, 0x204
	v_writelane_b32 v244, s9, 28
	s_cselect_b64 s[8:9], -1, 0
	v_writelane_b32 v244, s8, 29
	s_ashr_i32 s3, s24, 31
	s_ashr_i32 s47, s46, 31
	v_writelane_b32 v244, s9, 30
	v_writelane_b32 v244, s3, 31
	s_lshr_b32 s3, s3, 29
	s_add_i32 s3, s24, s3
	s_ashr_i32 s8, s3, 3
	s_and_b32 s3, s3, -8
	s_sub_i32 s10, s24, s3
	s_mul_i32 s3, s10, 0x73
	s_add_i32 s11, s3, 4
	s_and_b32 s73, s61, 0xffff
	s_add_u32 s12, s96, 0x200
	s_addc_u32 s13, s97, 0
	v_writelane_b32 v244, s12, 32
	s_mov_b32 s33, 0x800000
	s_mov_b64 s[44:45], 0x80
	v_writelane_b32 v244, s13, 33
	s_add_u32 s12, s96, 0x1000
	s_addc_u32 s13, s97, 0
	v_writelane_b32 v244, s12, 34
	s_waitcnt lgkmcnt(0)
	s_barrier
	v_writelane_b32 v244, s13, 35
	s_add_u32 s12, s96, 0x1100
	s_addc_u32 s13, s97, 0
	v_writelane_b32 v244, s12, 36
	s_nop 1
	v_writelane_b32 v244, s13, 37
	s_add_u32 s12, s96, 0x1200
	s_addc_u32 s13, s97, 0
	v_writelane_b32 v244, s12, 38
	s_nop 1
	v_writelane_b32 v244, s13, 39
	s_add_u32 s12, s96, 0x1300
	s_addc_u32 s13, s97, 0
	v_writelane_b32 v244, s12, 40
	s_cmp_eq_u32 s4, 15
	s_nop 0
	v_writelane_b32 v244, s13, 41
	s_cselect_b64 s[12:13], -1, 0
	v_writelane_b32 v244, s12, 42
	s_cmp_eq_u32 s4, 14
	s_nop 0
	v_writelane_b32 v244, s13, 43
	s_cselect_b64 s[12:13], -1, 0
	v_writelane_b32 v244, s12, 44
	s_cmp_eq_u32 s4, 13
	s_nop 0
	v_writelane_b32 v244, s13, 45
	s_cselect_b64 s[12:13], -1, 0
	v_writelane_b32 v244, s12, 46
	s_cmp_eq_u32 s4, 12
	s_nop 0
	v_writelane_b32 v244, s13, 47
	s_cselect_b64 s[12:13], -1, 0
	v_writelane_b32 v244, s12, 48
	s_cmp_eq_u32 s4, 11
	s_nop 0
	v_writelane_b32 v244, s13, 49
	s_cselect_b64 s[12:13], -1, 0
	v_writelane_b32 v244, s12, 50
	s_cmp_eq_u32 s4, 10
	s_nop 0
	v_writelane_b32 v244, s13, 51
	s_cselect_b64 s[12:13], -1, 0
	v_writelane_b32 v244, s12, 52
	s_cmp_eq_u32 s4, 9
	s_nop 0
	v_writelane_b32 v244, s13, 53
	s_cselect_b64 s[12:13], -1, 0
	v_writelane_b32 v244, s12, 54
	s_cmp_eq_u32 s4, 8
	s_nop 0
	v_writelane_b32 v244, s13, 55
	s_cselect_b64 s[12:13], -1, 0
	v_writelane_b32 v244, s12, 56
	s_cmp_eq_u32 s4, 7
	s_nop 0
	v_writelane_b32 v244, s13, 57
	s_cselect_b64 s[12:13], -1, 0
	v_writelane_b32 v244, s12, 58
	s_cmp_eq_u32 s4, 6
	s_nop 0
	v_writelane_b32 v244, s13, 59
	s_cselect_b64 s[12:13], -1, 0
	v_writelane_b32 v244, s12, 60
	s_cmp_eq_u32 s4, 5
	s_nop 0
	v_writelane_b32 v244, s13, 61
	s_cselect_b64 s[12:13], -1, 0
	v_writelane_b32 v244, s12, 62
	s_cmp_eq_u32 s4, 4
	s_nop 0
	v_writelane_b32 v244, s13, 63
	s_cselect_b64 s[12:13], -1, 0
	v_writelane_b32 v243, s12, 0
	s_cmp_eq_u32 s4, 3
	s_nop 0
	v_writelane_b32 v243, s13, 1
	s_cselect_b64 s[12:13], -1, 0
	v_writelane_b32 v243, s12, 2
	s_cmp_eq_u32 s4, 2
	s_nop 0
	v_writelane_b32 v243, s13, 3
	s_cselect_b64 s[12:13], -1, 0
	v_writelane_b32 v243, s12, 4
	s_cmp_eq_u32 s4, 1
	s_nop 0
	v_writelane_b32 v243, s13, 5
	s_cselect_b64 s[12:13], -1, 0
	v_writelane_b32 v243, s12, 6
	s_cmp_eq_u32 s4, 0
	s_nop 0
	v_writelane_b32 v243, s13, 7
	s_cselect_b64 s[12:13], -1, 0
	s_lshl_b32 s3, s4, 8
	s_add_u32 s3, s96, s3
	v_writelane_b32 v243, s12, 8
	s_addc_u32 s4, s97, 0
	s_nop 0
	v_writelane_b32 v243, s13, 9
	s_add_u32 s12, s3, 0x1400
	s_addc_u32 s13, s4, 0
	v_writelane_b32 v243, s12, 10
	s_nop 1
	v_writelane_b32 v243, s13, 11
	s_add_u32 s12, s3, 0x2400
	s_addc_u32 s13, s4, 0
	v_writelane_b32 v243, s12, 12
	s_nop 1
	v_writelane_b32 v243, s13, 13
	s_add_u32 s12, s96, 0x3400
	s_addc_u32 s13, s97, 0
	v_writelane_b32 v243, s12, 14
	s_nop 1
	v_writelane_b32 v243, s13, 15
	s_add_u32 s12, s96, 0x3500
	s_addc_u32 s13, s97, 0
	v_writelane_b32 v243, s12, 16
	s_cmp_eq_u32 s6, 0
	s_nop 0
	v_writelane_b32 v243, s13, 17
	s_cselect_b64 s[12:13], -1, 0
	s_cmp_lg_u32 s6, 0
	v_writelane_b32 v243, s12, 18
	s_cselect_b64 s[6:7], -1, 0
	s_cmpk_lt_i32 s24, 0x200
	v_writelane_b32 v243, s13, 19
	s_cselect_b64 s[12:13], -1, 0
	v_writelane_b32 v243, s12, 20
	s_and_b64 s[6:7], s[12:13], s[6:7]
	s_and_b32 s3, s24, 7
	s_lshl_b32 s3, s3, 6
	s_lshr_b32 s4, s24, 2
	s_and_b32 s4, s4, 0x3e
	s_or_b32 s3, s3, s4
	s_nop 0
	v_writelane_b32 v242, s3, 63
	s_lshl_b32 s3, s3, 5
	v_writelane_b32 v243, s13, 21
	v_writelane_b32 v243, s6, 22
	s_orn2_b32 s4, 0xfffff81f, s3
	s_nop 0
	v_writelane_b32 v243, s7, 23
	v_writelane_b32 v243, s4, 24
	v_writelane_b32 v243, s3, 25
	s_orn2_b32 s3, 0xfffff83f, s3
	s_cmpk_lt_i32 s24, 0x80
	v_writelane_b32 v243, s3, 26
	s_cselect_b64 s[6:7], -1, 0
	v_writelane_b32 v243, s6, 27
	s_add_i32 s3, s46, s24
	s_add_u32 s4, s50, 0x42c0000
	v_writelane_b32 v243, s7, 28
	v_writelane_b32 v243, s4, 29
	s_addc_u32 s4, s51, 0
	s_and_b32 s9, s63, 0xffff
	s_add_u32 s6, s50, 0x4200000
	v_writelane_b32 v243, s4, 30
	s_addc_u32 s7, s51, 0
	v_writelane_b32 v243, s6, 31
	s_add_u32 s4, s50, 0x42b4000
	s_nop 0
	v_writelane_b32 v243, s7, 32
	v_writelane_b32 v243, s4, 33
	s_addc_u32 s4, s51, 0
	v_writelane_b32 v243, s4, 34
	s_add_u32 s4, s50, 0x42b4600
	v_writelane_b32 v243, s4, 35
	s_addc_u32 s4, s51, 0
	s_cmpk_lt_i32 s24, 0x100
	v_writelane_b32 v243, s4, 36
	s_cselect_b64 s[6:7], -1, 0
	v_writelane_b32 v243, s6, 37
	s_lshl_b32 s4, s10, 5
	s_and_b32 s65, s59, 0xffff
	v_writelane_b32 v243, s7, 38
	s_cmp_lt_i32 s10, 4
	s_mul_i32 s6, s10, 0x74
	s_cselect_b32 s6, s6, s11
	s_add_i32 s6, s6, s8
	s_mul_hi_i32 s7, s6, 0x92492493
	s_add_i32 s7, s7, s6
	s_lshr_b32 s11, s7, 31
	s_ashr_i32 s7, s7, 6
	s_add_i32 s7, s7, s11
	s_mul_i32 s11, s7, 0x70
	s_lshl_b32 s12, s7, 3
	s_sub_i32 s11, s6, s11
	s_sub_i32 s6, 0x42, s12
	s_min_u32 s13, s6, 8
	s_cmp_lt_i32 s10, 0
	s_mul_i32 s10, s10, 33
	s_cselect_b32 s4, s10, s4
	s_add_i32 s4, s4, s8
	s_ashr_i32 s6, s4, 31
	s_lshr_b32 s6, s6, 27
	s_add_i32 s6, s4, s6
	s_and_b32 s7, s6, 0xffe0
	s_sub_i32 s4, s4, s7
	s_bfe_i32 s7, s4, 0x80000
	s_bfe_u32 s7, s7, 0x3000c
	s_add_i32 s7, s4, s7
	s_and_b32 s8, s7, 0xf8
	s_sub_i32 s4, s4, s8
	s_ashr_i32 s6, s6, 5
	s_bfe_i32 s7, s7, 0x80000
	s_lshl_b32 s6, s6, 3
	s_sext_i32_i16 s7, s7
	s_sext_i32_i8 s4, s4
	s_add_i32 s16, s6, s4
	s_ashr_i32 s4, s7, 3
	v_writelane_b32 v243, s4, 39
	s_lshr_b32 s4, s7, 3
	v_cvt_f32_ubyte0_e32 v2, s13
	s_bfe_i64 s[6:7], s[4:5], 0x100000
	v_cvt_f32_i32_e32 v1, s11
	v_rcp_iflag_f32_e32 v3, v2
	s_lshl_b64 s[6:7], s[6:7], 19
	s_ashr_i32 s17, s16, 31
	v_writelane_b32 v243, s6, 40
	s_mov_b32 s4, s16
	v_mul_f32_e32 v3, v1, v3
	v_writelane_b32 v243, s7, 41
	s_lshl_b64 s[6:7], s[16:17], 19
	v_writelane_b32 v243, s4, 42
	s_add_u32 s6, s62, s6
	s_addc_u32 s7, s63, s7
	v_writelane_b32 v243, s5, 43
	v_trunc_f32_e32 v3, v3
	s_add_u32 s16, s6, 0x40000
	v_writelane_b32 v243, s6, 44
	v_fma_f32 v1, -v3, v2, v1
	s_addc_u32 s17, s7, 0
	v_writelane_b32 v243, s7, 45
	v_cmp_ge_f32_e64 s[6:7], |v1|, v2
	v_cvt_i32_f32_e32 v1, v3
	s_ashr_i32 s4, s11, 30
	s_or_b32 s4, s4, 1
	s_and_b64 s[6:7], s[6:7], exec
	s_cselect_b32 s4, s4, 0
	v_readfirstlane_b32 s6, v1
	s_add_i32 s4, s6, s4
	s_mul_i32 s6, s4, s13
	s_sub_i32 s6, s11, s6
	v_writelane_b32 v243, s16, 46
	s_sext_i32_i8 s6, s6
	s_add_i32 s6, s12, s6
	v_writelane_b32 v243, s17, 47
	v_writelane_b32 v243, s6, 48
	s_lshr_b32 s6, s2, 25
	s_mul_i32 s6, s6, s0
	s_sub_i32 s6, 0x80, s6
	s_sub_i32 s7, s6, s0
	s_cmp_ge_u32 s6, s0
	s_cselect_b32 s6, s7, s6
	s_sub_i32 s7, s6, s0
	s_cmp_ge_u32 s6, s0
	s_cselect_b32 s6, s7, s6
	s_sub_i32 s3, s3, s6
	s_abs_i32 s6, s3
	s_mul_hi_u32 s2, s6, s2
	s_mul_i32 s2, s2, s0
	s_sub_i32 s2, s6, s2
	s_ashr_i32 s3, s3, 31
	s_sub_i32 s6, s2, s0
	s_cmp_ge_u32 s2, s0
	s_cselect_b32 s2, s6, s2
	s_sub_i32 s6, s2, s0
	s_cmp_ge_u32 s2, s0
	s_cselect_b32 s0, s6, s2
	s_xor_b32 s0, s0, s3
	s_sub_i32 s6, s0, s3
	s_cmpk_lt_i32 s6, 0x80
	s_cselect_b64 s[2:3], -1, 0
	v_writelane_b32 v243, s2, 49
	s_lshl_b32 s0, s1, 3
	s_lshl_b32 s18, s46, 7
	v_writelane_b32 v243, s3, 50
	s_sub_i32 s2, s5, s0
	v_writelane_b32 v243, s2, 51
	s_lshl_b32 s2, s46, 3
	s_sub_i32 s29, s2, s0
	s_lshl_b32 s0, s1, 7
	s_lshl_b32 s1, s24, 7
	v_writelane_b32 v243, s1, 52
	s_sub_i32 s1, s1, s0
	s_sub_i32 s19, s18, s0
	v_writelane_b32 v243, s1, 53
	s_add_u32 s0, s76, 8
	v_writelane_b32 v243, s0, 54
	s_addc_u32 s0, s77, 0
	s_ashr_i32 s7, s6, 31
	v_writelane_b32 v243, s0, 55
	s_lshl_b64 s[0:1], s[6:7], 14
	s_add_u32 s0, s60, s0
	s_addc_u32 s1, s61, s1
	s_add_u32 s0, s0, 0x4003e00
	s_addc_u32 s1, s1, 0
	v_writelane_b32 v243, s0, 56
	s_mov_b32 s8, s62
	v_mov_b32_e32 v1, 0x358637bd
	v_writelane_b32 v243, s1, 57
	s_lshl_b64 s[0:1], s[46:47], 14
	v_writelane_b32 v243, s0, 58
	s_nop 1
	v_writelane_b32 v243, s1, 59
	s_mov_b32 s0, s6
	v_writelane_b32 v243, s0, 60
	s_nop 1
	v_writelane_b32 v243, s1, 61
	s_lshl_b64 s[0:1], s[6:7], 13
	s_add_u32 s0, s62, s0
	s_addc_u32 s1, s63, s1
	s_add_u32 s0, s0, 0x2000000
	s_addc_u32 s1, s1, 0
	v_writelane_b32 v243, s0, 62
	s_nop 1
	v_writelane_b32 v243, s1, 63
	s_mov_b32 s1, 0
	v_writelane_b32 v242, s0, 0
	s_nop 1
	v_writelane_b32 v242, s1, 1
	v_writelane_b32 v242, s14, 2
	s_sext_i32_i8 s0, s4
	s_nop 0
	v_writelane_b32 v242, s15, 3
	v_writelane_b32 v242, s0, 4
	s_lshl_b32 s0, s24, 6
	v_writelane_b32 v242, s0, 5
	s_lshl_b32 s0, s46, 6
	v_writelane_b32 v242, s0, 6
	s_lshl_b32 s0, s24, 1
	v_writelane_b32 v242, s0, 7
	s_lshl_b32 s0, s46, 1
	v_writelane_b32 v242, s0, 8
	s_add_i32 s0, 32, 0x16020
	v_writelane_b32 v242, s0, 9
	s_add_i32 s0, 32, 0x16060
	v_writelane_b32 v242, s0, 10
	s_add_i32 s0, 32, 0x160a0
	v_writelane_b32 v242, s0, 11
	s_add_i32 s0, 32, 0x160e0
	v_writelane_b32 v242, s0, 12
	s_add_i32 s0, 32, 0x16120
	v_writelane_b32 v242, s0, 13
	s_add_i32 s0, 32, 0x16160
	v_writelane_b32 v242, s0, 14
	s_add_i32 s0, 32, 0x161a0
	v_writelane_b32 v242, s0, 15
	s_add_i32 s0, 32, 0x161e0
	v_writelane_b32 v242, s0, 16
	s_add_i32 s0, 32, 0x16030
	v_writelane_b32 v242, s0, 17
	s_add_i32 s0, 32, 0x16070
	v_writelane_b32 v242, s0, 18
	s_add_i32 s0, 32, 0x160b0
	v_writelane_b32 v242, s0, 19
	s_add_i32 s0, 32, 0x160f0
	v_writelane_b32 v242, s0, 20
	s_add_i32 s0, 32, 0x16130
	v_writelane_b32 v242, s0, 21
	s_add_i32 s0, 32, 0x16170
	v_writelane_b32 v242, s0, 22
	s_add_i32 s0, 32, 0x161b0
	v_writelane_b32 v242, s0, 23
	s_add_i32 s0, 32, 0x161f0
	v_writelane_b32 v242, s0, 24
	s_add_i32 s0, 32, 0x16010
	v_writelane_b32 v242, s0, 25
	s_add_i32 s0, 32, 0x16050
	v_writelane_b32 v242, s0, 26
	s_add_i32 s0, 32, 0x16090
	v_writelane_b32 v242, s0, 27
	s_add_i32 s0, 32, 0x160d0
	v_writelane_b32 v242, s0, 28
	s_add_i32 s0, 32, 0x16110
	v_writelane_b32 v242, s0, 29
	s_add_i32 s0, 32, 0x16150
	v_writelane_b32 v242, s0, 30
	s_add_i32 s0, 32, 0x16190
	v_writelane_b32 v242, s0, 31
	s_add_i32 s0, 32, 0x161d0
	v_writelane_b32 v242, s0, 32
	s_add_i32 s0, 32, 0x16040
	v_writelane_b32 v242, s0, 33
	s_add_i32 s0, 32, 0x16080
	v_writelane_b32 v242, s0, 34
	s_add_i32 s0, 32, 0x160c0
	v_writelane_b32 v242, s0, 35
	s_add_i32 s0, 32, 0x16100
	v_writelane_b32 v242, s0, 36
	s_add_i32 s0, 32, 0x16140
	v_writelane_b32 v242, s0, 37
	s_add_i32 s0, 32, 0x16180
	v_writelane_b32 v242, s0, 38
	s_add_i32 s0, 32, 0x161c0
	v_writelane_b32 v242, s0, 39
	s_mov_b32 s0, 0
	v_writelane_b32 v242, s0, 40
	s_lshl_b64 s[0:1], s[46:47], 13
	v_writelane_b32 v242, s0, 41
	s_movk_i32 s15, 0x7fff
	s_nop 0
	v_writelane_b32 v242, s1, 42
	v_writelane_b32 v242, s20, 43
	v_writelane_b32 v242, s21, 44
	v_writelane_b32 v242, s28, 45
	v_writelane_b32 v242, s29, 46
	s_mov_b64 s[0:1], -1
	v_writelane_b32 v242, s18, 47
	v_writelane_b32 v242, s19, 48
	s_branch .LBB0_431

.LBB0_797:
	s_add_i32 s5, s6, 1
	v_mov_b32_e32 v26, v0
	s_bitcmp0_b32 s5, 0
	s_cselect_b64 s[34:35], -1, 0
	s_bitcmp1_b32 s5, 0
	v_lshl_add_u32 v26, v26, 4, 32
	s_cselect_b32 s2, s5, s6
	v_add_u32_e32 v27, 0xd800, v26
	s_waitcnt vmcnt(8)
	ds_write_b128 v26, v[2:5] offset:55296
	ds_write_b128 v26, v[6:9] offset:63488
	ds_write_b128 v27, v[10:13] offset:16384
	ds_write_b128 v27, v[14:17] offset:24576
	ds_write_b128 v27, v[18:21] offset:32768
	ds_write_b128 v27, v[22:25] offset:40960
	s_lshl_b32 s7, s2, 5
	s_waitcnt lgkmcnt(0)
	s_barrier
	s_and_b32 s12, s7, 0x7e0
	s_sub_i32 s10, s7, 30
	s_ashr_i32 s11, s10, 31
	s_lshl_b64 s[10:11], s[10:11], 12
	s_add_u32 s10, s60, s10
	s_addc_u32 s11, s61, s11
	s_cmp_eq_u32 s12, 0
	s_cselect_b32 s13, 30, 0
	v_cmp_le_i32_e32 vcc, s13, v234
	v_mov_b32_e32 v2, 0
	v_mov_b32_e32 v3, 0
	v_mov_b32_e32 v4, 0
	v_mov_b32_e32 v5, 0
	s_and_saveexec_b64 s[2:3], vcc
	global_load_dwordx4 v[2:5], v241, s[10:11]
	s_or_b64 exec, exec, s[2:3]
	v_cmp_le_i32_e32 vcc, s13, v235
	v_mov_b32_e32 v6, 0
	v_mov_b32_e32 v7, 0
	v_mov_b32_e32 v8, 0
	v_mov_b32_e32 v9, 0
	s_and_saveexec_b64 s[2:3], vcc
	global_load_dwordx4 v[6:9], v245, s[10:11]
	s_or_b64 exec, exec, s[2:3]
	v_cmp_le_i32_e32 vcc, s13, v236
	v_mov_b32_e32 v10, 0
	v_mov_b32_e32 v11, 0
	v_mov_b32_e32 v12, 0
	v_mov_b32_e32 v13, 0
	s_and_saveexec_b64 s[2:3], vcc
	global_load_dwordx4 v[10:13], v246, s[10:11]
	s_or_b64 exec, exec, s[2:3]
	v_cmp_le_i32_e32 vcc, s13, v237
	v_mov_b32_e32 v14, 0
	v_mov_b32_e32 v15, 0
	v_mov_b32_e32 v16, 0
	v_mov_b32_e32 v17, 0
	s_and_saveexec_b64 s[2:3], vcc
	global_load_dwordx4 v[14:17], v247, s[10:11]
	s_or_b64 exec, exec, s[2:3]
	v_cmp_le_i32_e32 vcc, s13, v238
	v_mov_b32_e32 v18, 0
	v_mov_b32_e32 v19, 0
	v_mov_b32_e32 v20, 0
	v_mov_b32_e32 v21, 0
	s_and_saveexec_b64 s[2:3], vcc
	global_load_dwordx4 v[18:21], v252, s[10:11]
	s_or_b64 exec, exec, s[2:3]
	v_cmp_le_i32_e32 vcc, s13, v239
	v_mov_b32_e32 v22, 0
	v_mov_b32_e32 v23, 0
	v_mov_b32_e32 v24, 0
	v_mov_b32_e32 v25, 0
	s_and_saveexec_b64 s[2:3], vcc
	global_load_dwordx4 v[22:25], v253, s[10:11]
	s_or_b64 exec, exec, s[2:3]
	v_mov_b32_e32 v26, v0
	s_lshl_b32 s2, s6, 5
	v_ashrrev_i32_e32 v152, 6, v26
	v_lshlrev_b32_e32 v150, 2, v152
	v_and_b32_e32 v27, 63, v26
	s_ashr_i32 s3, s2, 31
	v_ashrrev_i32_e32 v151, 31, v150
	v_cmp_gt_u32_e64 s[38:39], 48, v27
	v_lshl_add_u64 v[148:149], v[150:151], 0, s[2:3]
	s_movk_i32 s3, 0x1000
	v_cndmask_b32_e64 v42, 47, v27, s[38:39]
	v_lshlrev_b64 v[26:27], 12, v[148:149]
	v_lshl_add_u64 v[82:83], s[60:61], 0, v[26:27]
	v_lshlrev_b32_e32 v154, 4, v42
	v_lshl_add_u64 v[56:57], v[82:83], 0, v[154:155]
	v_add_co_u32_e32 v26, vcc, s3, v56
	global_load_dwordx4 v[78:81], v[56:57], off offset:768
	global_load_dwordx4 v[38:41], v[56:57], off offset:2304
	v_addc_co_u32_e32 v27, vcc, 0, v57, vcc
	global_load_dwordx4 v[74:77], v[26:27], off offset:768
	global_load_dwordx4 v[34:37], v[26:27], off offset:2304
	v_add_co_u32_e32 v26, vcc, 0x2000, v56
	s_and_b32 s7, s2, 0x7e0
	s_nop 0
	v_addc_co_u32_e32 v27, vcc, 0, v57, vcc
	global_load_dwordx4 v[70:73], v[26:27], off offset:768
	global_load_dwordx4 v[30:33], v[26:27], off offset:2304
	v_add_co_u32_e32 v26, vcc, 0x3000, v56
	v_lshlrev_b32_e32 v86, 3, v42
	s_nop 0
	v_addc_co_u32_e32 v27, vcc, 0, v57, vcc
	global_load_dwordx4 v[58:61], v[26:27], off offset:768
	s_nop 0
	global_load_dwordx4 v[26:29], v[26:27], off offset:2304
	v_add_u32_e32 v63, s7, v150
	v_cmp_lt_i32_e32 vcc, 1, v63
	v_mov_b32_e32 v46, 0
	v_lshlrev_b32_e32 v84, 1, v86
	v_mov_b32_e32 v42, 0
	v_mov_b32_e32 v43, 0
	v_mov_b32_e32 v44, 0
	v_mov_b32_e32 v45, 0
	s_and_saveexec_b64 s[2:3], vcc
	s_cbranch_execz .LBB0_823
	v_mov_b32_e32 v85, v155
	v_lshl_add_u64 v[42:43], v[82:83], 0, v[84:85]
	v_add_co_u32_e32 v42, vcc, 0xfffff000, v42
	s_nop 1
	v_addc_co_u32_e32 v43, vcc, -1, v43, vcc
	global_load_dwordx4 v[42:45], v[42:43], off offset:-2560
